# back-edge rotation: loop counter, pointer advance, exit test and next-iteration LDS address set-up moved in front of the loop-bottom barrier; exit path has its own barrier copy
# baseline (speedup 1.0000x reference)
; #define GLOAD(kt_, KR, VR) do { _Pragma("unroll") for (int i = 0; i < KCH; ++i) if (krow_[i] < 64) KR[i] = *(const u32x4*)(kbase + (size_t)((kt_) * 64 + krow_[i]) * HK * DQ + kcol_[i]); \
;     VR = *(const u32x4*)(vbase + (size_t)(kt_) * 4096 + vrow * 64 + vcol); } while (0)
; #define LSTORE(buf_, KR, VR) do { _Pragma("unroll") for (int i = 0; i < KCH; ++i) if (krow_[i] < 64) *(u32x4*)(sK + (buf_) * 64 * KROW + krow_[i] * KROW + kcol_[i]) = KR[i]; \
;     u16* d_ = sV + (buf_) * 64 * VROW + vrow * VROW + (vcol >> 4) * 16 + ((vcol >> 3) & 1) * 4; u32x2 lo_ = {VR.x, VR.y}, hi_ = {VR.z, VR.w}; *(u32x2*)d_ = lo_; *(u32x2*)(d_ + 8) = hi_; } while (0)
; #define PP_BAR asm volatile("s_waitcnt lgkmcnt(0)\n\ts_barrier" ::: "memory")
; template <int DQ>
; DI void attn_dense_item(const u16* __restrict__ Q, int qh, const u16* __restrict__ Kp, int HK, int kh, const u16* __restrict__ Vt,
;                         int S, int s0, int qblk, u16* __restrict__ MER, int ocol, float* __restrict__ ssqo, int slot, unsigned char* smem) {
;     ...
;   for (int kt = 0; kt < nkt; kt += 2) {
;     const int sb = (kt & 2), nb = sb ^ 2;
;     TILE_X2(sb, kt == 0); TILE_Y2(sb);
;     if (kt + 2 < nkt) { LSTORE(nb, krA, vrA); LSTORE(nb + 1, krB, vrB); }
;     if (kt + 4 < nkt) { GLOAD(kt + 4, krA, vrA); GLOAD(kt + 5, krB, vrB); }
;     PP_BAR;
;   }
.LBB0_300:
	s_add_i32 s6, s14, -4
	s_and_b32 s6, s6, 2
	s_mul_i32 s7, s6, 0x3400
	v_add3_u32 v0, v198, s7, v199
	s_addk_i32 s7, 0x3400
	v_add3_u32 v225, v198, s7, v199
	s_mul_i32 s7, s6, 0x2400
	s_branch .Lmla_top
.LBB0_299:
	s_add_i32 s14, s14, 2
	v_lshl_add_u64 v[174:175], v[174:175], 0, s[58:59]
	v_lshl_add_u64 v[176:177], v[176:177], 0, s[60:61]
	s_cmp_ge_u32 s15, s23
	v_lshl_add_u64 v[178:179], v[178:179], 0, s[60:61]
	s_cbranch_scc1 .Lmla_exit_bar
	s_add_i32 s6, s14, -4
	s_and_b32 s6, s6, 2
	s_mul_i32 s7, s6, 0x3400
	v_add3_u32 v0, v198, s7, v199
	s_addk_i32 s7, 0x3400
	v_add3_u32 v225, v198, s7, v199
	s_mul_i32 s7, s6, 0x2400
	s_waitcnt lgkmcnt(0)
	s_barrier
.Lmla_top:
	ds_read_b128 v[226:229], v0
	ds_read_b128 v[230:233], v0 offset:32
	ds_read_b128 v[234:237], v0 offset:64
	ds_read_b128 v[238:241], v0 offset:96
	ds_read_b128 v[242:245], v0 offset:128
	ds_read_b128 v[162:165], v0 offset:160
	ds_read_b128 v[166:169], v0 offset:6656

; DI float xor32_sum(float x) { const auto r = __builtin_amdgcn_permlane32_swap(__float_as_uint(x), __float_as_uint(x), false, false); return __uint_as_float(r[0]) + __uint_as_float(r[1]); }
; template <int DQ>
; DI void attn_dense_item(const u16* __restrict__ Q, int qh, const u16* __restrict__ Kp, int HK, int kh, const u16* __restrict__ Vt,
;                         int S, int s0, int qblk, u16* __restrict__ MER, int ocol, float* __restrict__ ssqo, int slot, unsigned char* smem) {
;     ...
;   const float inv = 1.f / xor32_sum(lrun);
;   const int m = q0 + lr;
;   float ss = 0.f;
; #pragma unroll
;   for (int dvb = 0; dvb < 2; ++dvb) {
;     o[dvb] = o[dvb] * inv;
;     ss += sumsq16(o[dvb]);
;     st_sub_bf16(MER + (size_t)m * 1024 + ocol + dvb * 32, o[dvb], lh);
;   }
;   ss = xor32_sum(ss);
;   if (lh == 0) ssqo[(size_t)m * 16 + slot] = ss;
.Lmla_exit_bar:
	s_waitcnt lgkmcnt(0)
	s_barrier
.LBB0_321:
	v_add_f32_e32 v0, v74, v75
	v_add_f32_e32 v162, v76, v77
	v_add_f32_e32 v163, v78, v79
	v_add_f32_e32 v201, v80, v201
	v_add_f32_e32 v0, v81, v0
	v_add_f32_e32 v162, v82, v162
	v_add_f32_e32 v163, v83, v163
	v_add_f32_e32 v201, v84, v201
	v_add_f32_e32 v0, v85, v0
	v_add_f32_e32 v162, v86, v162
	v_add_f32_e32 v163, v87, v163
	v_add_f32_e32 v201, v88, v201
	v_add_f32_e32 v0, v89, v0
	v_add_f32_e32 v162, v90, v162
	v_add_f32_e32 v163, v91, v163
	v_add_f32_e32 v201, v92, v201
	v_add_f32_e32 v0, v93, v0
	v_add_f32_e32 v162, v94, v162
	v_add_f32_e32 v163, v95, v163
	v_add_f32_e32 v201, v96, v201
	v_add_f32_e32 v0, v97, v0
	v_add_f32_e32 v162, v98, v162
	v_add_f32_e32 v163, v99, v163
	v_add_f32_e32 v201, v100, v201
	v_add_f32_e32 v0, v101, v0
	v_add_f32_e32 v162, v102, v162
	v_add_f32_e32 v163, v103, v163
	v_add_f32_e32 v201, v104, v201
	v_add_f32_e32 v0, v105, v0
	v_add_f32_e32 v162, v106, v162
	v_add_f32_e32 v163, v107, v163
	v_add_f32_e32 v201, v108, v201
	v_add_f32_e32 v0, v109, v0
	v_add_f32_e32 v162, v110, v162
	v_add_f32_e32 v163, v111, v163
	v_add_f32_e32 v201, v112, v201
	v_add_f32_e32 v0, v113, v0
	v_add_f32_e32 v162, v246, v162
	v_add_f32_e32 v163, v202, v163
	v_add_f32_e32 v201, v203, v201
	v_add_f32_e32 v0, v204, v0
	v_add_f32_e32 v162, v205, v162
	v_add_f32_e32 v163, v206, v163
	v_add_f32_e32 v201, v207, v201
	v_add_f32_e32 v0, v208, v0
	v_add_f32_e32 v162, v209, v162
	v_add_f32_e32 v163, v210, v163
	v_add_f32_e32 v201, v211, v201
	v_add_f32_e32 v0, v212, v0
	v_add_f32_e32 v162, v213, v162
	v_add_f32_e32 v163, v214, v163
	v_add_f32_e32 v201, v215, v201
	v_add_f32_e32 v0, v216, v0
	v_add_f32_e32 v162, v217, v162
	v_add_f32_e32 v163, v218, v163
	v_add_f32_e32 v201, v219, v201
	v_add_f32_e32 v0, v220, v0
	v_add_f32_e32 v162, v221, v162
	v_add_f32_e32 v163, v222, v163
	v_add_f32_e32 v201, v223, v201
	v_add_f32_e32 v0, v224, v0
	v_add_f32_e32 v0, v162, v0
	v_add_f32_e32 v201, v163, v201
	v_add_f32_e32 v201, v0, v201
	v_mov_b32_e32 v0, v201
	s_nop 1
	v_permlane32_swap_b32_e32 v201, v0
	v_add_f32_e32 v0, v201, v0
	v_div_scale_f32 v34, s[0:1], v0, v0, 1.0
	v_rcp_f32_e32 v35, v34
	v_mov_b32_e32 v173, v1
	v_fma_f32 v36, -v34, v35, 1.0
	v_fmac_f32_e32 v35, v36, v35
	v_div_scale_f32 v36, vcc, 1.0, v0, 1.0
	v_mul_f32_e32 v37, v36, v35
	v_fma_f32 v38, -v34, v37, v36
	v_fmac_f32_e32 v37, v38, v35
	v_fma_f32 v34, -v34, v37, v36
	v_div_fmas_f32 v34, v34, v35, v37
	v_div_fixup_f32 v0, v34, v0, 1.0
	v_pk_mul_f32 v[18:19], v[18:19], v[0:1] op_sel_hi:[1,0]
	v_pk_mul_f32 v[2:3], v[2:3], v[0:1] op_sel_hi:[1,0]
	v_pk_mul_f32 v[32:33], v[32:33], v[0:1] op_sel_hi:[1,0]
	v_pk_mul_f32 v[30:31], v[30:31], v[0:1] op_sel_hi:[1,0]
	v_pk_mul_f32 v[28:29], v[28:29], v[0:1] op_sel_hi:[1,0]
	v_pk_mul_f32 v[26:27], v[26:27], v[0:1] op_sel_hi:[1,0]
	v_pk_mul_f32 v[24:25], v[24:25], v[0:1] op_sel_hi:[1,0]
	v_pk_mul_f32 v[22:23], v[22:23], v[0:1] op_sel_hi:[1,0]
	v_pk_mul_f32 v[20:21], v[20:21], v[0:1] op_sel_hi:[1,0]
	v_mul_f32_e32 v36, v19, v19
	v_pk_mul_f32 v[16:17], v[16:17], v[0:1] op_sel_hi:[1,0]
	v_pk_mul_f32 v[14:15], v[14:15], v[0:1] op_sel_hi:[1,0]
	v_pk_mul_f32 v[12:13], v[12:13], v[0:1] op_sel_hi:[1,0]
	v_pk_mul_f32 v[10:11], v[10:11], v[0:1] op_sel_hi:[1,0]
	v_pk_mul_f32 v[8:9], v[8:9], v[0:1] op_sel_hi:[1,0]
	v_pk_mul_f32 v[6:7], v[6:7], v[0:1] op_sel_hi:[1,0]
	v_pk_mul_f32 v[4:5], v[4:5], v[0:1] op_sel_hi:[1,0]
	v_mul_f32_e32 v0, v3, v3
	v_fmac_f32_e32 v36, v18, v18
	v_fmac_f32_e32 v0, v2, v2
	v_fmac_f32_e32 v36, v20, v20
	v_fmac_f32_e32 v0, v4, v4
	v_fmac_f32_e32 v36, v21, v21
	v_fmac_f32_e32 v0, v5, v5
	v_fmac_f32_e32 v36, v22, v22
	v_fmac_f32_e32 v0, v6, v6
	v_fmac_f32_e32 v36, v23, v23
	v_fmac_f32_e32 v0, v7, v7
	v_fmac_f32_e32 v36, v24, v24
	v_fmac_f32_e32 v0, v8, v8
	v_fmac_f32_e32 v36, v25, v25
	v_fmac_f32_e32 v0, v9, v9
	v_fmac_f32_e32 v36, v26, v26
	v_fmac_f32_e32 v0, v10, v10
	v_fmac_f32_e32 v36, v27, v27
	v_fmac_f32_e32 v0, v11, v11
	v_lshlrev_b64 v[34:35], 11, v[170:171]
	v_fmac_f32_e32 v36, v28, v28
	v_fmac_f32_e32 v0, v12, v12
	v_lshl_add_u64 v[34:35], s[88:89], 0, v[34:35]
	v_fmac_f32_e32 v36, v29, v29
	v_fmac_f32_e32 v0, v13, v13
	v_lshl_add_u64 v[34:35], s[12:13], 1, v[34:35]
	v_fmac_f32_e32 v36, v30, v30
	v_fmac_f32_e32 v0, v14, v14
	v_lshl_add_u64 v[34:35], v[34:35], 0, v[172:173]
	v_fmac_f32_e32 v36, v31, v31
	v_fmac_f32_e32 v0, v15, v15
	v_cvt_pk_bf16_f32 v2, v2, v3
	v_cvt_pk_bf16_f32 v3, v4, v5
	v_fmac_f32_e32 v36, v32, v32
	v_fmac_f32_e32 v0, v16, v16
	global_store_dwordx2 v[34:35], v[2:3], off offset:576
	v_cvt_pk_bf16_f32 v2, v6, v7
	v_cvt_pk_bf16_f32 v3, v8, v9
	v_fmac_f32_e32 v36, v33, v33
	v_cvt_pk_bf16_f32 v18, v18, v19
	v_cvt_pk_bf16_f32 v19, v20, v21
	v_fmac_f32_e32 v0, v17, v17
	global_store_dwordx2 v[34:35], v[2:3], off offset:592
	v_cvt_pk_bf16_f32 v2, v10, v11
	v_cvt_pk_bf16_f32 v3, v12, v13
	global_store_dwordx2 v[34:35], v[18:19], off offset:512
	v_cvt_pk_bf16_f32 v18, v22, v23
	v_cvt_pk_bf16_f32 v19, v24, v25
	v_add_f32_e32 v0, v36, v0
	global_store_dwordx2 v[34:35], v[2:3], off offset:608
	v_cvt_pk_bf16_f32 v2, v14, v15
	v_cvt_pk_bf16_f32 v3, v16, v17
	global_store_dwordx2 v[34:35], v[18:19], off offset:528
	v_cvt_pk_bf16_f32 v18, v26, v27
	v_cvt_pk_bf16_f32 v19, v28, v29
	global_store_dwordx2 v[34:35], v[2:3], off offset:624
	v_mov_b32_e32 v2, v0
	global_store_dwordx2 v[34:35], v[18:19], off offset:544
	v_cvt_pk_bf16_f32 v18, v30, v31
	v_cvt_pk_bf16_f32 v19, v32, v33
	v_permlane32_swap_b32_e32 v0, v2
	v_cmp_eq_u32_e32 vcc, 0, v191
	global_store_dwordx2 v[34:35], v[18:19], off offset:560
	s_and_saveexec_b64 s[0:1], vcc
	s_cbranch_execz .LBB0_256
	v_readlane_b32 s4, v250, 59
	v_add_f32_e32 v0, v0, v2
	v_lshlrev_b64 v[2:3], 6, v[170:171]
	v_readlane_b32 s5, v250, 60
	s_nop 1
	v_lshl_add_u64 v[2:3], s[4:5], 0, v[2:3]
	v_lshl_add_u64 v[2:3], s[10:11], 2, v[2:3]
	global_store_dword v[2:3], v0, off offset:16
	s_branch .LBB0_256

; #define GLOAD(kt_, KR, VR) do { _Pragma("unroll") for (int i = 0; i < KCH; ++i) if (krow_[i] < 64) KR[i] = *(const u32x4*)(kbase + (size_t)((kt_) * 64 + krow_[i]) * HK * DQ + kcol_[i]); \
;     VR = *(const u32x4*)(vbase + (size_t)(kt_) * 4096 + vrow * 64 + vcol); } while (0)
; #define LSTORE(buf_, KR, VR) do { _Pragma("unroll") for (int i = 0; i < KCH; ++i) if (krow_[i] < 64) *(u32x4*)(sK + (buf_) * 64 * KROW + krow_[i] * KROW + kcol_[i]) = KR[i]; \
;     u16* d_ = sV + (buf_) * 64 * VROW + vrow * VROW + (vcol >> 4) * 16 + ((vcol >> 3) & 1) * 4; u32x2 lo_ = {VR.x, VR.y}, hi_ = {VR.z, VR.w}; *(u32x2*)d_ = lo_; *(u32x2*)(d_ + 8) = hi_; } while (0)
; #define PP_BAR asm volatile("s_waitcnt lgkmcnt(0)\n\ts_barrier" ::: "memory")
; template <int DQ>
; DI void attn_dense_item(const u16* __restrict__ Q, int qh, const u16* __restrict__ Kp, int HK, int kh, const u16* __restrict__ Vt,
;                         int S, int s0, int qblk, u16* __restrict__ MER, int ocol, float* __restrict__ ssqo, int slot, unsigned char* smem) {
;     ...
;   for (int kt = 0; kt < nkt; kt += 2) {
;     const int sb = (kt & 2), nb = sb ^ 2;
;     TILE_X2(sb, kt == 0); TILE_Y2(sb);
;     if (kt + 2 < nkt) { LSTORE(nb, krA, vrA); LSTORE(nb + 1, krB, vrB); }
;     if (kt + 4 < nkt) { GLOAD(kt + 4, krA, vrA); GLOAD(kt + 5, krB, vrB); }
;     PP_BAR;
;   }
.LBB0_348:
	s_add_i32 s4, s12, -4
	s_and_b32 s4, s4, 2
	s_mul_i32 s5, s4, 0x2400
	v_add_u32_e32 v0, s5, v163
	s_branch .Lgqa_top
.LBB0_347:
	s_add_i32 s12, s12, 2
	v_lshl_add_u64 v[154:155], v[154:155], 0, s[62:63]
	s_cmp_ge_u32 s13, s23
	v_lshl_add_u64 v[156:157], v[156:157], 0, s[58:59]
	s_cbranch_scc1 .Lgqa_exit_bar
	s_add_i32 s4, s12, -4
	s_and_b32 s4, s4, 2
	s_mul_i32 s5, s4, 0x2400
	v_add_u32_e32 v0, s5, v163
	s_waitcnt lgkmcnt(0)
	s_barrier
.Lgqa_top:
	ds_read_b128 v[214:217], v0 offset:9216
	ds_read_b128 v[218:221], v0 offset:9248
	ds_read_b128 v[222:225], v0 offset:9280
	ds_read_b128 v[226:229], v0 offset:9312
	ds_read_b128 v[230:233], v0 offset:4608
	ds_read_b128 v[234:237], v0 offset:4640
	ds_read_b128 v[238:241], v0 offset:4672

; DI float xor32_sum(float x) { const auto r = __builtin_amdgcn_permlane32_swap(__float_as_uint(x), __float_as_uint(x), false, false); return __uint_as_float(r[0]) + __uint_as_float(r[1]); }
; template <int DQ>
; DI void attn_dense_item(const u16* __restrict__ Q, int qh, const u16* __restrict__ Kp, int HK, int kh, const u16* __restrict__ Vt,
;                         int S, int s0, int qblk, u16* __restrict__ MER, int ocol, float* __restrict__ ssqo, int slot, unsigned char* smem) {
;     ...
;   const float inv = 1.f / xor32_sum(lrun);
;   const int m = q0 + lr;
;   float ss = 0.f;
; #pragma unroll
;   for (int dvb = 0; dvb < 2; ++dvb) {
;     o[dvb] = o[dvb] * inv;
;     ss += sumsq16(o[dvb]);
;     st_sub_bf16(MER + (size_t)m * 1024 + ocol + dvb * 32, o[dvb], lh);
;   }
;   ss = xor32_sum(ss);
;   if (lh == 0) ssqo[(size_t)m * 16 + slot] = ss;
.Lgqa_exit_bar:
	s_waitcnt lgkmcnt(0)
	s_barrier
.LBB0_361:
	v_add_f32_e32 v0, v62, v63
	v_add_f32_e32 v146, v64, v65
	v_add_f32_e32 v147, v74, v75
	v_add_f32_e32 v165, v76, v165
	v_add_f32_e32 v0, v77, v0
	v_add_f32_e32 v146, v78, v146
	v_add_f32_e32 v147, v79, v147
	v_add_f32_e32 v165, v80, v165
	v_add_f32_e32 v0, v81, v0
	v_add_f32_e32 v146, v106, v146
	v_add_f32_e32 v147, v107, v147
	v_add_f32_e32 v165, v108, v165
	v_add_f32_e32 v0, v109, v0
	v_add_f32_e32 v146, v110, v146
	v_add_f32_e32 v147, v111, v147
	v_add_f32_e32 v165, v112, v165
	v_add_f32_e32 v0, v113, v0
	v_add_f32_e32 v146, v82, v146
	v_add_f32_e32 v147, v83, v147
	v_add_f32_e32 v165, v84, v165
	v_add_f32_e32 v0, v85, v0
	v_add_f32_e32 v146, v86, v146
	v_add_f32_e32 v147, v87, v147
	v_add_f32_e32 v165, v88, v165
	v_add_f32_e32 v0, v89, v0
	v_add_f32_e32 v146, v90, v146
	v_add_f32_e32 v147, v91, v147
	v_add_f32_e32 v165, v92, v165
	v_add_f32_e32 v0, v93, v0
	v_add_f32_e32 v146, v94, v146
	v_add_f32_e32 v147, v95, v147
	v_add_f32_e32 v165, v96, v165
	v_add_f32_e32 v0, v97, v0
	v_add_f32_e32 v146, v166, v146
	v_add_f32_e32 v147, v167, v147
	v_add_f32_e32 v165, v168, v165
	v_add_f32_e32 v0, v169, v0
	v_add_f32_e32 v146, v170, v146
	v_add_f32_e32 v147, v171, v147
	v_add_f32_e32 v165, v172, v165
	v_add_f32_e32 v0, v173, v0
	v_add_f32_e32 v146, v174, v146
	v_add_f32_e32 v147, v175, v147
	v_add_f32_e32 v165, v176, v165
	v_add_f32_e32 v0, v177, v0
	v_add_f32_e32 v146, v178, v146
	v_add_f32_e32 v147, v179, v147
	v_add_f32_e32 v165, v191, v165
	v_add_f32_e32 v0, v192, v0
	v_add_f32_e32 v146, v193, v146
	v_add_f32_e32 v147, v194, v147
	v_add_f32_e32 v165, v195, v165
	v_add_f32_e32 v0, v196, v0
	v_add_f32_e32 v146, v197, v146
	v_add_f32_e32 v147, v198, v147
	v_add_f32_e32 v165, v199, v165
	v_add_f32_e32 v0, v200, v0
	v_add_f32_e32 v146, v201, v146
	v_add_f32_e32 v147, v202, v147
	v_add_f32_e32 v165, v203, v165
	v_add_f32_e32 v0, v204, v0
	v_add_f32_e32 v0, v146, v0
	v_add_f32_e32 v165, v147, v165
	v_add_f32_e32 v165, v0, v165
	v_mov_b32_e32 v0, v165
	s_nop 1
	v_permlane32_swap_b32_e32 v165, v0
	v_add_f32_e32 v0, v165, v0
	v_div_scale_f32 v34, s[0:1], v0, v0, 1.0
	v_rcp_f32_e32 v35, v34
	s_lshl_b32 s0, s6, 6
	s_ashr_i32 s1, s0, 31
	v_mov_b32_e32 v153, v1
	v_fma_f32 v36, -v34, v35, 1.0
	v_fmac_f32_e32 v35, v36, v35
	v_div_scale_f32 v36, vcc, 1.0, v0, 1.0
	v_mul_f32_e32 v37, v36, v35
	v_fma_f32 v38, -v34, v37, v36
	v_fmac_f32_e32 v37, v38, v35
	v_fma_f32 v34, -v34, v37, v36
	v_div_fmas_f32 v34, v34, v35, v37
	v_div_fixup_f32 v0, v34, v0, 1.0
	v_pk_mul_f32 v[18:19], v[18:19], v[0:1] op_sel_hi:[1,0]
	v_pk_mul_f32 v[2:3], v[2:3], v[0:1] op_sel_hi:[1,0]
	v_pk_mul_f32 v[32:33], v[32:33], v[0:1] op_sel_hi:[1,0]
	v_pk_mul_f32 v[30:31], v[30:31], v[0:1] op_sel_hi:[1,0]
	v_pk_mul_f32 v[28:29], v[28:29], v[0:1] op_sel_hi:[1,0]
	v_pk_mul_f32 v[26:27], v[26:27], v[0:1] op_sel_hi:[1,0]
	v_pk_mul_f32 v[24:25], v[24:25], v[0:1] op_sel_hi:[1,0]
	v_pk_mul_f32 v[22:23], v[22:23], v[0:1] op_sel_hi:[1,0]
	v_pk_mul_f32 v[20:21], v[20:21], v[0:1] op_sel_hi:[1,0]
	v_mul_f32_e32 v36, v19, v19
	v_pk_mul_f32 v[16:17], v[16:17], v[0:1] op_sel_hi:[1,0]
	v_pk_mul_f32 v[14:15], v[14:15], v[0:1] op_sel_hi:[1,0]
	v_pk_mul_f32 v[12:13], v[12:13], v[0:1] op_sel_hi:[1,0]
	v_pk_mul_f32 v[10:11], v[10:11], v[0:1] op_sel_hi:[1,0]
	v_pk_mul_f32 v[8:9], v[8:9], v[0:1] op_sel_hi:[1,0]
	v_pk_mul_f32 v[6:7], v[6:7], v[0:1] op_sel_hi:[1,0]
	v_pk_mul_f32 v[4:5], v[4:5], v[0:1] op_sel_hi:[1,0]
	v_mul_f32_e32 v0, v3, v3
	v_fmac_f32_e32 v36, v18, v18
	v_fmac_f32_e32 v0, v2, v2
	v_fmac_f32_e32 v36, v20, v20
	v_fmac_f32_e32 v0, v4, v4
	v_fmac_f32_e32 v36, v21, v21
	v_fmac_f32_e32 v0, v5, v5
	v_fmac_f32_e32 v36, v22, v22
	v_fmac_f32_e32 v0, v6, v6
	v_fmac_f32_e32 v36, v23, v23
	v_fmac_f32_e32 v0, v7, v7
	v_fmac_f32_e32 v36, v24, v24
	v_fmac_f32_e32 v0, v8, v8
	v_fmac_f32_e32 v36, v25, v25
	v_fmac_f32_e32 v0, v9, v9
	v_fmac_f32_e32 v36, v26, v26
	v_fmac_f32_e32 v0, v10, v10
	v_fmac_f32_e32 v36, v27, v27
	v_fmac_f32_e32 v0, v11, v11
	v_lshlrev_b64 v[34:35], 11, v[150:151]
	v_fmac_f32_e32 v36, v28, v28
	v_fmac_f32_e32 v0, v12, v12
	v_lshl_add_u64 v[34:35], s[88:89], 0, v[34:35]
	v_fmac_f32_e32 v36, v29, v29
	v_fmac_f32_e32 v0, v13, v13
	v_lshl_add_u64 v[34:35], s[0:1], 1, v[34:35]
	v_fmac_f32_e32 v36, v30, v30
	v_fmac_f32_e32 v0, v14, v14
	v_lshl_add_u64 v[34:35], v[34:35], 0, v[152:153]
	v_fmac_f32_e32 v36, v31, v31
	v_fmac_f32_e32 v0, v15, v15
	v_cvt_pk_bf16_f32 v2, v2, v3
	v_cvt_pk_bf16_f32 v3, v4, v5
	v_fmac_f32_e32 v36, v32, v32
	v_fmac_f32_e32 v0, v16, v16
	global_store_dwordx2 v[34:35], v[2:3], off offset:1344
	v_cvt_pk_bf16_f32 v2, v6, v7
	v_cvt_pk_bf16_f32 v3, v8, v9
	v_fmac_f32_e32 v36, v33, v33
	v_cvt_pk_bf16_f32 v18, v18, v19
	v_cvt_pk_bf16_f32 v19, v20, v21
	v_fmac_f32_e32 v0, v17, v17
	global_store_dwordx2 v[34:35], v[2:3], off offset:1360
	v_cvt_pk_bf16_f32 v2, v10, v11
	v_cvt_pk_bf16_f32 v3, v12, v13
	global_store_dwordx2 v[34:35], v[18:19], off offset:1280
	v_cvt_pk_bf16_f32 v18, v22, v23
	v_cvt_pk_bf16_f32 v19, v24, v25
	v_add_f32_e32 v0, v36, v0
	global_store_dwordx2 v[34:35], v[2:3], off offset:1376
	v_cvt_pk_bf16_f32 v2, v14, v15
	v_cvt_pk_bf16_f32 v3, v16, v17
	global_store_dwordx2 v[34:35], v[18:19], off offset:1296
	v_cvt_pk_bf16_f32 v18, v26, v27
	v_cvt_pk_bf16_f32 v19, v28, v29
	global_store_dwordx2 v[34:35], v[2:3], off offset:1392
	v_mov_b32_e32 v2, v0
	global_store_dwordx2 v[34:35], v[18:19], off offset:1312
	v_cvt_pk_bf16_f32 v18, v30, v31
	v_cvt_pk_bf16_f32 v19, v32, v33
	v_permlane32_swap_b32_e32 v0, v2
	v_cmp_eq_u32_e32 vcc, 0, v158
	global_store_dwordx2 v[34:35], v[18:19], off offset:1328
	s_and_saveexec_b64 s[0:1], vcc
	s_cbranch_execz .LBB0_324
	v_readlane_b32 s4, v250, 59
	v_add_f32_e32 v0, v0, v2
	v_lshlrev_b64 v[2:3], 6, v[150:151]
	v_readlane_b32 s5, v250, 60
	s_nop 1
	v_lshl_add_u64 v[2:3], s[4:5], 0, v[2:3]
	v_lshl_add_u64 v[2:3], s[6:7], 2, v[2:3]
	global_store_dword v[2:3], v0, off offset:40
	s_branch .LBB0_324
